# diff attention: V tile units permuted in LDS so each V fragment is one conflict-free ds_read_b128 (was 2-way conflicted ds_read2_b64)
# speedup vs baseline: 1.0357x; 1.0029x over previous
.LBB0_745:
	v_mov_b32_e32 v177, v192
	v_lshl_add_u64 v[18:19], v[172:173], 1, v[18:19]
	v_ashrrev_i32_e32 v22, 31, v177
	v_lshrrev_b32_e32 v22, 28, v22
	v_add_u32_e32 v22, v177, v22
	v_ashrrev_i32_e32 v50, 4, v22
	v_and_b32_e32 v22, -16, v22
	v_sub_u32_e32 v58, v177, v22
	v_lshlrev_b32_e32 v24, 3, v58
	v_ashrrev_i32_e32 v25, 31, v24
	v_add_u32_e32 v34, 0x200, v177
	v_and_b32_e32 v113, 31, v177
	v_bfe_u32 v51, v177, 5, 1
	v_lshlrev_b64 v[52:53], 1, v[24:25]
	v_ashrrev_i32_e32 v24, 31, v34
	v_mad_u64_u32 v[18:19], s[24:25], v113, s28, v[18:19]
	v_lshlrev_b32_e32 v174, 4, v51
	v_mov_b32_e32 v175, v112
	v_lshrrev_b32_e32 v24, 28, v24
	v_lshl_add_u64 v[46:47], v[18:19], 0, v[174:175]
	v_add_u32_e32 v24, v34, v24
	global_load_dwordx4 v[18:21], v[46:47], off offset:96
	v_ashrrev_i32_e32 v54, 4, v24
	v_and_b32_e32 v24, -16, v24
	v_sub_u32_e32 v59, v34, v24
	v_lshlrev_b32_e32 v26, 3, v59
	v_ashrrev_i32_e32 v62, 3, v177
	v_lshlrev_b32_e32 v32, 3, v177
	v_ashrrev_i32_e32 v63, 3, v34
	v_mad_i64_i32 v[22:23], s[24:25], s22, v50, 0
	v_mad_i64_i32 v[24:25], s[24:25], s22, v54, 0
	v_ashrrev_i32_e32 v27, 31, v26
	v_mad_i64_i32 v[30:31], s[24:25], s20, v62, 0
	v_and_b32_e32 v55, 56, v32
	v_mad_i64_i32 v[34:35], s[24:25], s20, v63, 0
	v_lshl_add_u64 v[22:23], v[22:23], 1, v[180:181]
	v_lshl_add_u64 v[24:25], v[24:25], 1, v[180:181]
	v_lshlrev_b64 v[56:57], 1, v[26:27]
	v_lshl_add_u64 v[30:31], v[30:31], 1, v[16:17]
	v_lshlrev_b32_e32 v32, 1, v55
	v_mov_b32_e32 v33, v112
	v_lshl_add_u64 v[34:35], v[34:35], 1, v[16:17]
	v_lshl_add_u64 v[22:23], v[22:23], 0, v[52:53]
	v_lshl_add_u64 v[26:27], v[24:25], 0, v[56:57]
	v_lshl_add_u64 v[30:31], v[30:31], 0, v[32:33]
	v_lshl_add_u64 v[34:35], v[34:35], 0, v[32:33]
	global_load_dwordx4 v[22:25], v[22:23], off
	s_nop 0
	global_load_dwordx4 v[26:29], v[26:27], off
	s_nop 0
	global_load_dwordx4 v[30:33], v[30:31], off
	s_nop 0
	global_load_dwordx4 v[34:37], v[34:35], off
	s_nop 0
	global_load_dwordx4 v[38:41], v[46:47], off offset:64
	global_load_dwordx4 v[42:45], v[46:47], off offset:32
	s_nop 0
	global_load_dwordx4 v[46:49], v[46:47], off
	v_lshlrev_b32_e32 v201, 4, v58
	v_lshlrev_b32_e32 v213, 4, v59
	s_mov_b32 s24, 0x3e38aa3b
	s_movk_i32 s1, 0x48
	v_lshlrev_b32_e32 v176, 3, v51
	v_mul_lo_u32 v51, v62, s1
	v_add_lshl_u32 v191, v51, v55, 1
	v_mul_lo_u32 v51, v63, s1
	s_movk_i32 s1, 0x110
	v_mul_lo_u32 v195, v50, s1
	v_mul_lo_u32 v202, v54, s1
	s_lshl_b32 s1, s20, 1
	v_add_lshl_u32 v193, v51, v55, 1
	v_and_b32_e32 v60, 1, v192
	v_lshlrev_b32_e32 v60, 3, v60
	v_sub_u32_e32 v191, v191, v60
	v_sub_u32_e32 v193, v193, v60
	v_ashrrev_i32_e32 v55, 31, v54
	v_lshl_add_u64 v[16:17], v[16:17], 0, s[94:95]
	v_ashrrev_i32_e32 v51, 31, v50
	v_add_u32_e32 v64, 0, v191
	v_add_u32_e32 v65, 0, v193
	v_add3_u32 v66, 0, v201, v195
	v_add3_u32 v67, 0, v213, v202
	v_mov_b32_e32 v190, 0
	v_and_b32_e32 v175, 63, v177
	v_mul_u32_u24_e32 v214, 0x90, v113
	s_add_i32 s0, s0, 1
	s_mov_b32 s5, 0
	v_mov_b32_e32 v68, v190
	v_mov_b32_e32 v69, v190
	v_mov_b32_e32 v70, v190
	v_mov_b32_e32 v71, v190
	v_mov_b32_e32 v72, v190
	v_mov_b32_e32 v73, v190
	v_mov_b32_e32 v74, v190
	v_mov_b32_e32 v75, v190
	v_mov_b32_e32 v76, v190
	v_mov_b32_e32 v77, v190
	v_mov_b32_e32 v78, v190
	v_mov_b32_e32 v79, v190
	s_waitcnt vmcnt(0)
	ds_write_b128 v66, v[22:25]
	ds_write_b128 v67, v[26:29]
	ds_write_b64 v64, v[30:31] offset:17408
	ds_write_b64 v64, v[32:33] offset:17424
	ds_write_b64 v65, v[34:35] offset:17408
	ds_write_b64 v65, v[36:37] offset:17424
	v_lshlrev_b32_e32 v58, 16, v18
	v_and_b32_e32 v59, 0xffff0000, v18
	v_lshlrev_b32_e32 v18, 16, v19
	v_and_b32_e32 v19, 0xffff0000, v19
	v_pk_mul_f32 v[18:19], v[18:19], s[24:25] op_sel_hi:[1,0]
	v_lshlrev_b32_e32 v60, 16, v20
	v_cvt_pk_bf16_f32 v115, v18, v19
	v_lshlrev_b32_e32 v18, 16, v21
	v_and_b32_e32 v19, 0xffff0000, v21
	v_pk_mul_f32 v[18:19], v[18:19], s[24:25] op_sel_hi:[1,0]
	v_and_b32_e32 v61, 0xffff0000, v20
	v_cvt_pk_bf16_f32 v117, v18, v19
	v_lshlrev_b32_e32 v18, 16, v38
	v_and_b32_e32 v19, 0xffff0000, v38
	v_pk_mul_f32 v[18:19], v[18:19], s[24:25] op_sel_hi:[1,0]
	v_pk_mul_f32 v[58:59], v[58:59], s[24:25] op_sel_hi:[1,0]
	v_cvt_pk_bf16_f32 v118, v18, v19
	v_lshlrev_b32_e32 v18, 16, v39
	v_and_b32_e32 v19, 0xffff0000, v39
	v_pk_mul_f32 v[18:19], v[18:19], s[24:25] op_sel_hi:[1,0]
	v_pk_mul_f32 v[60:61], v[60:61], s[24:25] op_sel_hi:[1,0]
	v_cvt_pk_bf16_f32 v119, v18, v19
	v_lshlrev_b32_e32 v18, 16, v40
	v_and_b32_e32 v19, 0xffff0000, v40
	v_pk_mul_f32 v[18:19], v[18:19], s[24:25] op_sel_hi:[1,0]
	v_cvt_pk_bf16_f32 v114, v58, v59
	v_cvt_pk_bf16_f32 v120, v18, v19
	v_lshlrev_b32_e32 v18, 16, v41
	v_and_b32_e32 v19, 0xffff0000, v41
	v_pk_mul_f32 v[18:19], v[18:19], s[24:25] op_sel_hi:[1,0]
	v_cvt_pk_bf16_f32 v116, v60, v61
	v_cvt_pk_bf16_f32 v121, v18, v19
	v_lshlrev_b32_e32 v18, 16, v42
	v_and_b32_e32 v19, 0xffff0000, v42
	v_pk_mul_f32 v[18:19], v[18:19], s[24:25] op_sel_hi:[1,0]
	v_mov_b32_e32 v22, v190
	v_cvt_pk_bf16_f32 v122, v18, v19
	v_lshlrev_b32_e32 v18, 16, v43
	v_and_b32_e32 v19, 0xffff0000, v43
	v_pk_mul_f32 v[18:19], v[18:19], s[24:25] op_sel_hi:[1,0]
	v_mov_b32_e32 v23, v190
	v_cvt_pk_bf16_f32 v123, v18, v19
	v_lshlrev_b32_e32 v18, 16, v44
	v_and_b32_e32 v19, 0xffff0000, v44
	v_pk_mul_f32 v[18:19], v[18:19], s[24:25] op_sel_hi:[1,0]
	v_mov_b32_e32 v24, v190
	v_cvt_pk_bf16_f32 v124, v18, v19
	v_lshlrev_b32_e32 v18, 16, v45
	v_and_b32_e32 v19, 0xffff0000, v45
	v_pk_mul_f32 v[18:19], v[18:19], s[24:25] op_sel_hi:[1,0]
	v_mov_b32_e32 v25, v190
	v_cvt_pk_bf16_f32 v125, v18, v19
	v_lshlrev_b32_e32 v18, 16, v46
	v_and_b32_e32 v19, 0xffff0000, v46
	v_pk_mul_f32 v[18:19], v[18:19], s[24:25] op_sel_hi:[1,0]
	v_mov_b32_e32 v26, v190
	v_cvt_pk_bf16_f32 v126, v18, v19
	v_lshlrev_b32_e32 v18, 16, v47
	v_and_b32_e32 v19, 0xffff0000, v47
	v_pk_mul_f32 v[18:19], v[18:19], s[24:25] op_sel_hi:[1,0]
	v_mov_b32_e32 v27, v190
	v_cvt_pk_bf16_f32 v127, v18, v19
	v_lshlrev_b32_e32 v18, 16, v48
	v_and_b32_e32 v19, 0xffff0000, v48
	v_pk_mul_f32 v[18:19], v[18:19], s[24:25] op_sel_hi:[1,0]
	v_mov_b32_e32 v28, v190
	v_cvt_pk_bf16_f32 v128, v18, v19
	v_lshlrev_b32_e32 v18, 16, v49
	v_and_b32_e32 v19, 0xffff0000, v49
	v_pk_mul_f32 v[18:19], v[18:19], s[24:25] op_sel_hi:[1,0]
	v_mov_b32_e32 v29, v190
	v_cvt_pk_bf16_f32 v129, v18, v19
	v_mul_u32_u24_e32 v18, 0x88, v113
	v_add_lshl_u32 v216, v18, v172, 1
	v_and_b32_e32 v18, 7, v177
	v_lshlrev_b32_e32 v18, 4, v18
	v_mov_b32_e32 v19, v112
	v_mad_i64_i32 v[20:21], s[20:21], s1, v63, v[18:19]
	v_mad_i64_i32 v[18:19], s[20:21], s1, v62, v[18:19]
	v_lshl_add_u64 v[182:183], v[16:17], 0, v[20:21]
	v_lshl_add_u64 v[184:185], v[16:17], 0, v[18:19]
	v_lshl_add_u64 v[16:17], v[54:55], 1, v[168:169]
	v_mad_u64_u32 v[186:187], s[20:21], s22, v16, v[56:57]
	v_mad_i32_i24 v187, s22, v17, v187
	v_lshl_add_u64 v[16:17], v[50:51], 1, v[168:169]
	v_mad_u64_u32 v[188:189], s[24:25], s22, v16, v[52:53]
	v_add_u32_e32 v215, 0x2200, v216
	s_lshl_b32 s20, s22, 7
	s_mov_b32 s21, s96
	v_mad_i32_i24 v189, s22, v17, v189
	v_mov_b32_e32 v16, 0
	v_mov_b32_e32 v17, v190
	v_mov_b32_e32 v18, v190
	v_mov_b32_e32 v19, v190
	v_mov_b32_e32 v20, v190
	v_mov_b32_e32 v21, v190
	v_mov_b32_e32 v30, v190
	v_mov_b32_e32 v31, v190
	v_mov_b32_e32 v32, 0
	v_mov_b32_e32 v33, v190
	v_mov_b32_e32 v34, v190
	v_mov_b32_e32 v35, v190
	v_mov_b32_e32 v36, v190
	v_mov_b32_e32 v37, v190
	v_mov_b32_e32 v38, v190
	v_mov_b32_e32 v39, v190
	v_mov_b32_e32 v40, v190
	v_mov_b32_e32 v41, v190
	v_mov_b32_e32 v42, v190
	v_mov_b32_e32 v43, v190
	v_mov_b32_e32 v44, v190
	v_mov_b32_e32 v45, v190
	v_mov_b32_e32 v46, v190
	v_mov_b32_e32 v47, v190
	v_mov_b32_e32 v48, 0
	v_mov_b32_e32 v49, v190
	v_mov_b32_e32 v50, v190
	v_mov_b32_e32 v51, v190
	v_mov_b32_e32 v52, v190
	v_mov_b32_e32 v53, v190
	v_mov_b32_e32 v54, v190
	v_mov_b32_e32 v55, v190
	v_mov_b32_e32 v56, v190
	v_mov_b32_e32 v57, v190
	v_mov_b32_e32 v58, v190
	v_mov_b32_e32 v59, v190
	v_mov_b32_e32 v60, v190
	v_mov_b32_e32 v61, v190
	v_mov_b32_e32 v62, v190
	v_mov_b32_e32 v63, v190
	v_mov_b32_e32 v64, 0
	v_mov_b32_e32 v65, v190
	v_mov_b32_e32 v66, v190
	v_mov_b32_e32 v67, v190
	s_waitcnt lgkmcnt(0)
	s_barrier
.LBB0_746:
	v_lshl_add_u64 v[80:81], v[180:181], 0, v[188:189]
	v_lshl_add_u64 v[82:83], v[180:181], 0, v[186:187]
	global_load_dwordx4 v[130:133], v[80:81], off
	global_load_dwordx4 v[134:137], v[82:83], off
	global_load_dwordx4 v[138:141], v[184:185], off
	global_load_dwordx4 v[142:145], v[182:183], off
	s_add_i32 s1, s5, 1
	s_bitcmp1_b32 s5, 0
	s_cselect_b32 s5, 0x8c00, 0
	s_add_i32 s5, s5, 0
	v_add_u32_e32 v84, s5, v174
	v_add_u32_e32 v85, v84, v216
	v_add_u32_e32 v84, v84, v215
	ds_read_b128 v[80:83], v85
	ds_read_b128 v[218:221], v85 offset:32
	ds_read_b128 v[222:225], v85 offset:64
	ds_read_b128 v[226:229], v85 offset:96
	ds_read_b128 v[230:233], v84
	ds_read_b128 v[234:237], v84 offset:32
	ds_read_b128 v[238:241], v84 offset:64
	ds_read_b128 v[242:245], v84 offset:96
	v_add3_u32 v84, s5, v176, v214
	v_add_u32_e32 v84, v84, v176
	v_add_u32_e32 v164, 0x4000, v84
	v_add_u32_e32 v165, 0x5000, v84
	v_add_u32_e32 v166, 0x6800, v84
	v_add_u32_e32 v167, 0x7800, v84
	ds_read_b128 v[146:149], v164 offset:1024
	ds_read_b128 v[150:153], v165 offset:1536
	ds_read_b128 v[154:157], v166
	ds_read_b128 v[158:161], v167 offset:512
	s_setprio 1
	s_waitcnt lgkmcnt(11)
	v_mfma_f32_32x32x16_bf16 v[96:111], v[80:83], v[126:129], v[0:15]
	s_waitcnt lgkmcnt(7)
	v_mfma_f32_32x32x16_bf16 v[80:95], v[230:233], v[126:129], v[0:15]
	v_mfma_f32_32x32x16_bf16 v[96:111], v[218:221], v[122:125], v[96:111]
	s_waitcnt lgkmcnt(6)
	v_mfma_f32_32x32x16_bf16 v[80:95], v[234:237], v[122:125], v[80:95]
	v_mfma_f32_32x32x16_bf16 v[96:111], v[222:225], v[118:121], v[96:111]
	s_waitcnt lgkmcnt(5)
	v_mfma_f32_32x32x16_bf16 v[80:95], v[238:241], v[118:121], v[80:95]
	v_mfma_f32_32x32x16_bf16 v[96:111], v[226:229], v[114:117], v[96:111]
	s_waitcnt lgkmcnt(4)
	v_mfma_f32_32x32x16_bf16 v[80:95], v[242:245], v[114:117], v[80:95]
	s_setprio 0
	s_nop 8
	v_exp_f32_e32 v96, v96
	v_exp_f32_e32 v97, v97
	v_exp_f32_e32 v98, v98
	v_exp_f32_e32 v99, v99
	v_add_f32_e32 v194, 0, v96
	v_exp_f32_e32 v100, v100
	v_add_f32_e32 v194, v97, v194
	v_exp_f32_e32 v101, v101
	v_add_f32_e32 v194, v98, v194
	v_exp_f32_e32 v102, v102
	v_add_f32_e32 v194, v99, v194
	v_exp_f32_e32 v103, v103
	v_add_f32_e32 v194, v100, v194
	v_exp_f32_e32 v209, v104
	v_add_f32_e32 v194, v101, v194
	v_add_f32_e32 v194, v102, v194
	v_add_f32_e32 v194, v103, v194
	v_add_f32_e32 v104, v209, v194
	v_exp_f32_e32 v194, v105
	v_exp_f32_e32 v217, v106
	v_exp_f32_e32 v218, v107
	v_exp_f32_e32 v219, v108
	v_add_f32_e32 v104, v194, v104
	v_exp_f32_e32 v220, v109
	v_add_f32_e32 v104, v217, v104
	v_exp_f32_e32 v221, v110
	v_add_f32_e32 v104, v218, v104
	v_exp_f32_e32 v222, v111
	v_add_f32_e32 v104, v219, v104
	v_exp_f32_e32 v223, v80
	v_add_f32_e32 v104, v220, v104
	v_exp_f32_e32 v224, v81
	v_add_f32_e32 v104, v221, v104
	v_exp_f32_e32 v225, v82
	v_add_f32_e32 v104, v222, v104
	v_exp_f32_e32 v226, v83
	v_add_f32_e32 v80, v223, v104
	v_exp_f32_e32 v227, v84
	v_add_f32_e32 v80, v224, v80
	v_exp_f32_e32 v228, v85
	v_add_f32_e32 v80, v225, v80
	v_exp_f32_e32 v229, v86
	v_add_f32_e32 v80, v226, v80
	v_exp_f32_e32 v230, v87
	v_add_f32_e32 v80, v227, v80
	v_exp_f32_e32 v231, v88
	v_add_f32_e32 v80, v228, v80
	v_exp_f32_e32 v232, v89
	v_add_f32_e32 v80, v229, v80
	v_exp_f32_e32 v233, v90
	v_add_f32_e32 v80, v230, v80
	v_exp_f32_e32 v234, v91
	v_add_f32_e32 v80, v231, v80
	v_exp_f32_e32 v235, v92
	v_add_f32_e32 v80, v232, v80
	v_exp_f32_e32 v236, v93
	v_add_f32_e32 v80, v233, v80
	v_exp_f32_e32 v237, v94
	v_add_f32_e32 v80, v234, v80
	v_exp_f32_e32 v238, v95
	v_add_f32_e32 v80, v235, v80
	v_add_f32_e32 v80, v236, v80
	v_add_f32_e32 v80, v237, v80
	v_add_f32_e32 v80, v238, v80
	v_add_f32_e32 v190, v190, v80
	ds_read_b128 v[80:83], v164 offset:1056
	ds_read_b128 v[84:87], v165 offset:1568
	ds_read_b128 v[88:91], v166 offset:32
	ds_read_b128 v[92:95], v167 offset:544
	v_cvt_pk_bf16_f32 v96, v96, v97
	v_cvt_pk_bf16_f32 v97, v98, v99
	v_cvt_pk_bf16_f32 v98, v100, v101
	v_cvt_pk_bf16_f32 v99, v102, v103
	s_setprio 1
	s_waitcnt lgkmcnt(7)
	v_mfma_f32_32x32x16_bf16 v[64:79], v[146:149], v[96:99], v[64:79]
	s_waitcnt lgkmcnt(6)
	v_mfma_f32_32x32x16_bf16 v[48:63], v[150:153], v[96:99], v[48:63]
	s_waitcnt lgkmcnt(5)
	v_mfma_f32_32x32x16_bf16 v[32:47], v[154:157], v[96:99], v[32:47]
	s_waitcnt lgkmcnt(4)
	v_mfma_f32_32x32x16_bf16 v[16:31], v[158:161], v[96:99], v[16:31]
	s_setprio 0
	ds_read_b128 v[96:99], v164 offset:1088
	ds_read_b128 v[100:103], v165 offset:1600
	ds_read_b128 v[104:107], v166 offset:64
	ds_read_b128 v[108:111], v167 offset:576
	v_cvt_pk_bf16_f32 v146, v209, v194
	v_cvt_pk_bf16_f32 v147, v217, v218
	v_cvt_pk_bf16_f32 v148, v219, v220
	v_cvt_pk_bf16_f32 v149, v221, v222
	s_setprio 1
	s_waitcnt lgkmcnt(7)
	v_mfma_f32_32x32x16_bf16 v[64:79], v[80:83], v[146:149], v[64:79]
	s_waitcnt lgkmcnt(6)
	v_mfma_f32_32x32x16_bf16 v[48:63], v[84:87], v[146:149], v[48:63]
	s_waitcnt lgkmcnt(5)
	v_mfma_f32_32x32x16_bf16 v[32:47], v[88:91], v[146:149], v[32:47]
	s_waitcnt lgkmcnt(4)
	v_mfma_f32_32x32x16_bf16 v[16:31], v[92:95], v[146:149], v[16:31]
	s_setprio 0
	ds_read_b128 v[80:83], v164 offset:1120
	ds_read_b128 v[84:87], v165 offset:1632
	ds_read_b128 v[88:91], v166 offset:96
	ds_read_b128 v[92:95], v167 offset:608
	v_cvt_pk_bf16_f32 v146, v223, v224
	v_cvt_pk_bf16_f32 v147, v225, v226
	v_cvt_pk_bf16_f32 v148, v227, v228
	v_cvt_pk_bf16_f32 v149, v229, v230
	s_setprio 1
	s_waitcnt lgkmcnt(7)
	v_mfma_f32_32x32x16_bf16 v[64:79], v[96:99], v[146:149], v[64:79]
	s_waitcnt lgkmcnt(6)
	v_mfma_f32_32x32x16_bf16 v[48:63], v[100:103], v[146:149], v[48:63]
	s_waitcnt lgkmcnt(5)
	v_mfma_f32_32x32x16_bf16 v[32:47], v[104:107], v[146:149], v[32:47]
	s_waitcnt lgkmcnt(4)
	v_mfma_f32_32x32x16_bf16 v[16:31], v[108:111], v[146:149], v[16:31]
	s_setprio 0
	v_cvt_pk_bf16_f32 v96, v231, v232
	v_cvt_pk_bf16_f32 v97, v233, v234
	v_cvt_pk_bf16_f32 v98, v235, v236
	v_cvt_pk_bf16_f32 v99, v237, v238
	s_setprio 1
	s_waitcnt lgkmcnt(3)
	v_mfma_f32_32x32x16_bf16 v[64:79], v[80:83], v[96:99], v[64:79]
	s_waitcnt lgkmcnt(2)
	v_mfma_f32_32x32x16_bf16 v[48:63], v[84:87], v[96:99], v[48:63]
	s_waitcnt lgkmcnt(1)
	v_mfma_f32_32x32x16_bf16 v[32:47], v[88:91], v[96:99], v[32:47]
	s_waitcnt lgkmcnt(0)
	v_mfma_f32_32x32x16_bf16 v[16:31], v[92:95], v[96:99], v[16:31]
	s_setprio 0
	s_bitcmp1_b32 s1, 0
	s_cselect_b32 s5, 0x8c00, 0
	s_add_i32 s22, s5, 0
	v_add3_u32 v80, s22, v201, v195
	v_lshl_add_u64 v[182:183], v[182:183], 0, s[94:95]
	v_lshl_add_u64 v[184:185], v[184:185], 0, s[94:95]
	v_lshl_add_u64 v[180:181], v[180:181], 0, s[20:21]
	s_cmp_eq_u32 s0, s1
	s_mov_b32 s5, s1
	v_add3_u32 v81, s22, v213, v202
	v_add_u32_e32 v82, s22, v191
	v_add_u32_e32 v83, s22, v193
	s_waitcnt vmcnt(3)
	ds_write_b128 v80, v[130:133]
	s_waitcnt vmcnt(2)
	ds_write_b128 v81, v[134:137]
	s_waitcnt vmcnt(1)
	ds_write_b64 v82, v[138:139] offset:17408
	ds_write_b64 v82, v[140:141] offset:17424
	s_waitcnt vmcnt(0)
	ds_write_b64 v83, v[142:143] offset:17408
	ds_write_b64 v83, v[144:145] offset:17424
	s_waitcnt lgkmcnt(0)
	s_barrier
	s_cbranch_scc0 .LBB0_746
	v_add_u32_e32 v84, s22, v174
	v_add_u32_e32 v85, v84, v216
	v_add_u32_e32 v84, v84, v215
	ds_read_b128 v[80:83], v85
	ds_read_b128 v[146:149], v85 offset:32
	ds_read_b128 v[150:153], v85 offset:64
	ds_read_b128 v[154:157], v85 offset:96
	ds_read_b128 v[158:161], v84
	ds_read_b128 v[180:183], v84 offset:32
	ds_read_b128 v[184:187], v84 offset:64
	ds_read_b128 v[216:219], v84 offset:96
	v_add3_u32 v84, s22, v176, v214
	v_add_u32_e32 v84, v84, v176
	v_add_u32_e32 v164, 0x4000, v84
	v_add_u32_e32 v165, 0x5000, v84
	v_add_u32_e32 v166, 0x6800, v84
	v_add_u32_e32 v167, 0x7800, v84
	ds_read_b128 v[130:133], v164 offset:1024
	ds_read_b128 v[134:137], v165 offset:1536
	ds_read_b128 v[138:141], v166
	ds_read_b128 v[142:145], v167 offset:512
	s_setprio 1
	s_waitcnt lgkmcnt(11)
	v_mfma_f32_32x32x16_bf16 v[96:111], v[80:83], v[126:129], v[0:15]
	s_waitcnt lgkmcnt(7)
	v_mfma_f32_32x32x16_bf16 v[80:95], v[158:161], v[126:129], v[0:15]
	s_waitcnt lgkmcnt(6)
	v_mfma_f32_32x32x16_bf16 v[80:95], v[180:183], v[122:125], v[80:95]
	v_mfma_f32_32x32x16_bf16 v[96:111], v[146:149], v[122:125], v[96:111]
	s_waitcnt lgkmcnt(5)
	v_mfma_f32_32x32x16_bf16 v[80:95], v[184:187], v[118:121], v[80:95]
	v_mfma_f32_32x32x16_bf16 v[96:111], v[150:153], v[118:121], v[96:111]
	s_waitcnt lgkmcnt(4)
	v_mfma_f32_32x32x16_bf16 v[80:95], v[216:219], v[114:117], v[80:95]
	v_mfma_f32_32x32x16_bf16 v[96:111], v[154:157], v[114:117], v[96:111]
	s_setprio 0
	s_nop 10
	v_exp_f32_e32 v96, v96
	v_exp_f32_e32 v97, v97
	v_exp_f32_e32 v98, v98
	v_exp_f32_e32 v99, v99
	v_add_f32_e32 v114, 0, v96
	v_exp_f32_e32 v100, v100
	v_add_f32_e32 v114, v97, v114
	v_exp_f32_e32 v101, v101
	v_add_f32_e32 v114, v98, v114
	v_exp_f32_e32 v102, v102
	v_add_f32_e32 v114, v99, v114
	v_exp_f32_e32 v103, v103
	v_add_f32_e32 v114, v100, v114
	v_exp_f32_e32 v115, v104
	v_add_f32_e32 v114, v101, v114
	v_add_f32_e32 v114, v102, v114
	v_add_f32_e32 v114, v103, v114
	v_add_f32_e32 v104, v115, v114
	v_exp_f32_e32 v114, v105
	v_exp_f32_e32 v116, v106
	v_exp_f32_e32 v117, v107
	v_exp_f32_e32 v118, v108
	v_add_f32_e32 v104, v114, v104
	v_exp_f32_e32 v119, v109
	v_add_f32_e32 v104, v116, v104
	v_exp_f32_e32 v120, v110
	v_add_f32_e32 v104, v117, v104
	v_exp_f32_e32 v121, v111
	v_add_f32_e32 v104, v118, v104
	v_exp_f32_e32 v122, v80
	v_add_f32_e32 v104, v119, v104
	v_exp_f32_e32 v123, v81
	v_add_f32_e32 v104, v120, v104
	v_exp_f32_e32 v124, v82
	v_add_f32_e32 v104, v121, v104
	v_exp_f32_e32 v125, v83
	v_add_f32_e32 v80, v122, v104
	v_exp_f32_e32 v126, v84
	v_add_f32_e32 v80, v123, v80
	v_exp_f32_e32 v127, v85
	v_add_f32_e32 v80, v124, v80
	v_exp_f32_e32 v128, v86
	v_add_f32_e32 v80, v125, v80
	v_exp_f32_e32 v129, v87
	v_add_f32_e32 v80, v126, v80
	v_exp_f32_e32 v146, v88
	v_add_f32_e32 v80, v127, v80
	v_exp_f32_e32 v147, v89
	v_add_f32_e32 v80, v128, v80
	v_exp_f32_e32 v148, v90
	v_add_f32_e32 v80, v129, v80
	v_exp_f32_e32 v149, v91
	v_add_f32_e32 v80, v146, v80
	v_exp_f32_e32 v150, v92
	v_add_f32_e32 v80, v147, v80
	v_exp_f32_e32 v151, v93
	v_add_f32_e32 v80, v148, v80
	v_exp_f32_e32 v152, v94
	v_add_f32_e32 v80, v149, v80
	v_exp_f32_e32 v153, v95
	v_add_f32_e32 v80, v150, v80
	v_add_f32_e32 v80, v151, v80
	v_add_f32_e32 v80, v152, v80
	v_add_f32_e32 v80, v153, v80
	v_add_f32_e32 v154, v190, v80
	ds_read_b128 v[80:83], v164 offset:1056
	ds_read_b128 v[84:87], v165 offset:1568
	ds_read_b128 v[88:91], v166 offset:32
	ds_read_b128 v[92:95], v167 offset:544
	v_cvt_pk_bf16_f32 v96, v96, v97
	v_cvt_pk_bf16_f32 v97, v98, v99
	v_cvt_pk_bf16_f32 v98, v100, v101
	v_cvt_pk_bf16_f32 v99, v102, v103
	s_setprio 1
	s_waitcnt lgkmcnt(7)
	v_mfma_f32_32x32x16_bf16 v[64:79], v[130:133], v[96:99], v[64:79]
	s_waitcnt lgkmcnt(6)
	v_mfma_f32_32x32x16_bf16 v[48:63], v[134:137], v[96:99], v[48:63]
	s_waitcnt lgkmcnt(5)
	v_mfma_f32_32x32x16_bf16 v[32:47], v[138:141], v[96:99], v[32:47]
	s_waitcnt lgkmcnt(4)
	v_mfma_f32_32x32x16_bf16 v[16:31], v[142:145], v[96:99], v[16:31]
	s_setprio 0
	ds_read_b128 v[96:99], v164 offset:1088
	ds_read_b128 v[100:103], v165 offset:1600
	ds_read_b128 v[104:107], v166 offset:64
	ds_read_b128 v[108:111], v167 offset:576
	v_cvt_pk_bf16_f32 v114, v115, v114
	v_cvt_pk_bf16_f32 v115, v116, v117
	v_cvt_pk_bf16_f32 v116, v118, v119
	v_cvt_pk_bf16_f32 v117, v120, v121
	s_setprio 1
	s_waitcnt lgkmcnt(7)
	v_mfma_f32_32x32x16_bf16 v[64:79], v[80:83], v[114:117], v[64:79]
	s_waitcnt lgkmcnt(6)
	v_mfma_f32_32x32x16_bf16 v[48:63], v[84:87], v[114:117], v[48:63]
	s_waitcnt lgkmcnt(5)
	v_mfma_f32_32x32x16_bf16 v[32:47], v[88:91], v[114:117], v[32:47]
	s_waitcnt lgkmcnt(4)
	v_mfma_f32_32x32x16_bf16 v[16:31], v[92:95], v[114:117], v[16:31]
	s_setprio 0
	ds_read_b128 v[80:83], v164 offset:1120
	ds_read_b128 v[84:87], v165 offset:1632
	ds_read_b128 v[88:91], v166 offset:96
	ds_read_b128 v[92:95], v167 offset:608
	v_cvt_pk_bf16_f32 v114, v122, v123
	v_cvt_pk_bf16_f32 v115, v124, v125
	v_cvt_pk_bf16_f32 v116, v126, v127
	v_cvt_pk_bf16_f32 v117, v128, v129
	s_setprio 1
	s_waitcnt lgkmcnt(7)
	v_mfma_f32_32x32x16_bf16 v[64:79], v[96:99], v[114:117], v[64:79]
	s_waitcnt lgkmcnt(6)
	v_mfma_f32_32x32x16_bf16 v[48:63], v[100:103], v[114:117], v[48:63]
	s_waitcnt lgkmcnt(5)
	v_mfma_f32_32x32x16_bf16 v[32:47], v[104:107], v[114:117], v[32:47]
	s_waitcnt lgkmcnt(4)
	v_mfma_f32_32x32x16_bf16 v[16:31], v[108:111], v[114:117], v[16:31]
	s_setprio 0
	v_cvt_pk_bf16_f32 v96, v146, v147
	v_cvt_pk_bf16_f32 v97, v148, v149
	v_cvt_pk_bf16_f32 v98, v150, v151
	v_cvt_pk_bf16_f32 v99, v152, v153
	s_setprio 1
	s_waitcnt lgkmcnt(3)
	v_mfma_f32_32x32x16_bf16 v[64:79], v[80:83], v[96:99], v[64:79]
	s_waitcnt lgkmcnt(2)
	v_mfma_f32_32x32x16_bf16 v[48:63], v[84:87], v[96:99], v[48:63]
	s_waitcnt lgkmcnt(1)
	v_mfma_f32_32x32x16_bf16 v[32:47], v[88:91], v[96:99], v[32:47]
	s_waitcnt lgkmcnt(0)
	v_mfma_f32_32x32x16_bf16 v[16:31], v[92:95], v[96:99], v[16:31]
	s_setprio 0
	v_mov_b32_e32 v80, v192
	s_barrier
	v_ashrrev_i32_e32 v81, 6, v177
	v_lshlrev_b32_e32 v80, 2, v80
	v_bitop3_b32 v80, v80, s33, v203 bitop3:0x6c
	ds_bpermute_b32 v80, v80, v154
	s_waitcnt lgkmcnt(0)
	v_add_f32_e32 v80, v154, v80
	v_div_scale_f32 v82, s[0:1], v80, v80, 1.0
	v_rcp_f32_e32 v83, v82
	v_div_scale_f32 v84, vcc, 1.0, v80, 1.0
	v_fma_f32 v85, -v82, v83, 1.0
	v_fmac_f32_e32 v83, v85, v83
	v_mul_f32_e32 v85, v84, v83
	v_fma_f32 v86, -v82, v85, v84
	v_fmac_f32_e32 v85, v86, v83
	v_fma_f32 v82, -v82, v85, v84
	v_div_fmas_f32 v82, v82, v83, v85
	v_div_fixup_f32 v84, v82, v80, 1.0
	v_cmp_lt_i32_e32 vcc, 3, v81
	v_lshlrev_b32_e32 v80, 2, v175
	s_and_saveexec_b64 s[20:21], vcc
	s_cbranch_execz .LBB0_749
	v_lshlrev_b32_e32 v82, 14, v81
	v_add3_u32 v82, 0, v80, v82
	v_add_u32_e32 v83, 0xffff0000, v82
	v_mul_f32_e32 v85, v64, v84
	ds_write_b32 v83, v85
	v_mul_f32_e32 v83, v65, v84
	v_add_u32_e32 v85, 0xffff0100, v82
	ds_write_b32 v85, v83
	v_mul_f32_e32 v83, v66, v84
	v_add_u32_e32 v85, 0xffff0200, v82
	ds_write_b32 v85, v83
	v_mul_f32_e32 v83, v67, v84
	v_add_u32_e32 v85, 0xffff0300, v82
	ds_write_b32 v85, v83
	v_mul_f32_e32 v83, v68, v84
	v_add_u32_e32 v85, 0xffff0400, v82
	ds_write_b32 v85, v83
	v_mul_f32_e32 v83, v69, v84
	v_add_u32_e32 v85, 0xffff0500, v82
	ds_write_b32 v85, v83
	v_mul_f32_e32 v83, v70, v84
	v_add_u32_e32 v85, 0xffff0600, v82
	ds_write_b32 v85, v83
	v_mul_f32_e32 v83, v71, v84
	v_add_u32_e32 v85, 0xffff0700, v82
	ds_write_b32 v85, v83
	v_mul_f32_e32 v83, v72, v84
	v_add_u32_e32 v85, 0xffff0800, v82
	ds_write_b32 v85, v83
	v_mul_f32_e32 v83, v73, v84
	v_add_u32_e32 v85, 0xffff0900, v82
	ds_write_b32 v85, v83
	v_mul_f32_e32 v83, v74, v84
	v_add_u32_e32 v85, 0xffff0a00, v82
	ds_write_b32 v85, v83
	v_mul_f32_e32 v83, v75, v84
	v_add_u32_e32 v85, 0xffff0b00, v82
	ds_write_b32 v85, v83
	v_mul_f32_e32 v83, v76, v84
	v_add_u32_e32 v85, 0xffff0c00, v82
	ds_write_b32 v85, v83
	v_mul_f32_e32 v83, v77, v84
	v_add_u32_e32 v85, 0xffff0d00, v82
	ds_write_b32 v85, v83
	v_mul_f32_e32 v83, v78, v84
	v_add_u32_e32 v85, 0xffff0e00, v82
	ds_write_b32 v85, v83
	v_mul_f32_e32 v83, v79, v84
	v_add_u32_e32 v85, 0xffff0f00, v82
	ds_write_b32 v85, v83
	v_add_u32_e32 v83, 0xffff1000, v82
	v_mul_f32_e32 v85, v48, v84
	ds_write_b32 v83, v85
	v_mul_f32_e32 v83, v49, v84
	v_add_u32_e32 v85, 0xffff1100, v82
	ds_write_b32 v85, v83
	v_mul_f32_e32 v83, v50, v84
	v_add_u32_e32 v85, 0xffff1200, v82
	ds_write_b32 v85, v83
	v_mul_f32_e32 v83, v51, v84
	v_add_u32_e32 v85, 0xffff1300, v82
	ds_write_b32 v85, v83
	v_mul_f32_e32 v83, v52, v84
	v_add_u32_e32 v85, 0xffff1400, v82
	ds_write_b32 v85, v83
	v_mul_f32_e32 v83, v53, v84
	v_add_u32_e32 v85, 0xffff1500, v82
	ds_write_b32 v85, v83
	v_mul_f32_e32 v83, v54, v84
	v_add_u32_e32 v85, 0xffff1600, v82
	ds_write_b32 v85, v83
	v_mul_f32_e32 v83, v55, v84
	v_add_u32_e32 v85, 0xffff1700, v82
	ds_write_b32 v85, v83
	v_mul_f32_e32 v83, v56, v84
	v_add_u32_e32 v85, 0xffff1800, v82
	ds_write_b32 v85, v83
	v_mul_f32_e32 v83, v57, v84
	v_add_u32_e32 v85, 0xffff1900, v82
	ds_write_b32 v85, v83
	v_mul_f32_e32 v83, v58, v84
	v_add_u32_e32 v85, 0xffff1a00, v82
	ds_write_b32 v85, v83
	v_mul_f32_e32 v83, v59, v84
	v_add_u32_e32 v85, 0xffff1b00, v82
	ds_write_b32 v85, v83
	v_mul_f32_e32 v83, v60, v84
	v_add_u32_e32 v85, 0xffff1c00, v82
	ds_write_b32 v85, v83
	v_mul_f32_e32 v83, v61, v84
	v_add_u32_e32 v85, 0xffff1d00, v82
	ds_write_b32 v85, v83
	v_mul_f32_e32 v83, v62, v84
	v_add_u32_e32 v85, 0xffff1e00, v82
	ds_write_b32 v85, v83
	v_mul_f32_e32 v83, v63, v84
	v_add_u32_e32 v85, 0xffff1f00, v82
	ds_write_b32 v85, v83
	v_add_u32_e32 v83, 0xffff2000, v82
	v_mul_f32_e32 v85, v32, v84
	ds_write_b32 v83, v85
	v_mul_f32_e32 v83, v33, v84
	v_add_u32_e32 v85, 0xffff2100, v82
	ds_write_b32 v85, v83
	v_mul_f32_e32 v83, v34, v84
	v_add_u32_e32 v85, 0xffff2200, v82
	ds_write_b32 v85, v83
	v_mul_f32_e32 v83, v35, v84
	v_add_u32_e32 v85, 0xffff2300, v82
	ds_write_b32 v85, v83
	v_mul_f32_e32 v83, v36, v84
	v_add_u32_e32 v85, 0xffff2400, v82
	ds_write_b32 v85, v83
	v_mul_f32_e32 v83, v37, v84
	v_add_u32_e32 v85, 0xffff2500, v82
	ds_write_b32 v85, v83
	v_mul_f32_e32 v83, v38, v84
	v_add_u32_e32 v85, 0xffff2600, v82
	ds_write_b32 v85, v83
	v_mul_f32_e32 v83, v39, v84
	v_add_u32_e32 v85, 0xffff2700, v82
	ds_write_b32 v85, v83
	v_mul_f32_e32 v83, v40, v84
	v_add_u32_e32 v85, 0xffff2800, v82
	ds_write_b32 v85, v83
	v_mul_f32_e32 v83, v41, v84
	v_add_u32_e32 v85, 0xffff2900, v82
	ds_write_b32 v85, v83
	v_mul_f32_e32 v83, v42, v84
	v_add_u32_e32 v85, 0xffff2a00, v82
	ds_write_b32 v85, v83
	v_mul_f32_e32 v83, v43, v84
	v_add_u32_e32 v85, 0xffff2b00, v82
	ds_write_b32 v85, v83
	v_mul_f32_e32 v83, v44, v84
	v_add_u32_e32 v85, 0xffff2c00, v82
	ds_write_b32 v85, v83
	v_mul_f32_e32 v83, v45, v84
	v_add_u32_e32 v85, 0xffff2d00, v82
	ds_write_b32 v85, v83
	v_mul_f32_e32 v83, v46, v84
	v_add_u32_e32 v85, 0xffff2e00, v82
	ds_write_b32 v85, v83
	v_mul_f32_e32 v83, v47, v84
	v_add_u32_e32 v85, 0xffff2f00, v82
	ds_write_b32 v85, v83
	v_add_u32_e32 v83, 0xffff3000, v82
	v_mul_f32_e32 v85, v16, v84
	ds_write_b32 v83, v85
	v_mul_f32_e32 v83, v17, v84
	v_add_u32_e32 v85, 0xffff3100, v82
	ds_write_b32 v85, v83
	v_mul_f32_e32 v83, v18, v84
	v_add_u32_e32 v85, 0xffff3200, v82
	ds_write_b32 v85, v83
	v_mul_f32_e32 v83, v19, v84
	v_add_u32_e32 v85, 0xffff3300, v82
	ds_write_b32 v85, v83
	v_mul_f32_e32 v83, v20, v84
	v_add_u32_e32 v85, 0xffff3400, v82
	ds_write_b32 v85, v83
	v_mul_f32_e32 v83, v21, v84
	v_add_u32_e32 v85, 0xffff3500, v82
	ds_write_b32 v85, v83
	v_mul_f32_e32 v83, v22, v84
	v_add_u32_e32 v85, 0xffff3600, v82
	ds_write_b32 v85, v83
	v_mul_f32_e32 v83, v23, v84
	v_add_u32_e32 v85, 0xffff3700, v82
	ds_write_b32 v85, v83
	v_mul_f32_e32 v83, v24, v84
	v_add_u32_e32 v85, 0xffff3800, v82
	ds_write_b32 v85, v83
	v_mul_f32_e32 v83, v25, v84
	v_add_u32_e32 v85, 0xffff3900, v82
	ds_write_b32 v85, v83
	v_mul_f32_e32 v83, v26, v84
	v_add_u32_e32 v85, 0xffff3a00, v82
	ds_write_b32 v85, v83
	v_mul_f32_e32 v83, v27, v84
	v_add_u32_e32 v85, 0xffff3b00, v82
	ds_write_b32 v85, v83
	v_mul_f32_e32 v83, v28, v84
	v_add_u32_e32 v85, 0xffff3c00, v82
	ds_write_b32 v85, v83
	v_mul_f32_e32 v83, v29, v84
	v_add_u32_e32 v85, 0xffff3d00, v82
	ds_write_b32 v85, v83
	v_mul_f32_e32 v83, v30, v84
	v_add_u32_e32 v85, 0xffff3e00, v82
	ds_write_b32 v85, v83
	v_mul_f32_e32 v83, v31, v84
	v_add_u32_e32 v82, 0xffff3f00, v82
	ds_write_b32 v82, v83
